# P13 unit order 4x8 per XCD round with the rounds reversed (most recently written hidden-activation rows first)
# speedup vs baseline: 1.0026x; 1.0026x over previous
.LBB0_1531:
	s_cmp_lt_i32 s74, 14
	s_cselect_b64 s[4:5], -1, 0
	s_and_b64 s[6:7], s[4:5], s[0:1]
	s_andn2_b64 vcc, exec, s[6:7]
	s_cbranch_vccnz .LBB0_1570
	s_and_b32 s4, s78, 0xffffffc0
	s_cmpk_lt_i32 s2, 0x400
	s_cselect_b64 s[0:1], -1, 0
	s_add_i32 s5, 0, 0x250a8
	v_mov_b32_e32 v0, s5
	ds_read_b64 v[2:3], v0
	v_mbcnt_lo_u32_b32 v0, -1, 0
	v_mbcnt_hi_u32_b32 v8, -1, v0
	v_add_u32_e32 v0, s4, v8
	s_and_b64 vcc, exec, s[0:1]
	s_waitcnt lgkmcnt(0)
	v_readfirstlane_b32 s5, v3
	v_readfirstlane_b32 s14, v2
	v_readfirstlane_b32 s4, v0
	s_cbranch_vccz .LBB0_1534
	s_ashr_i32 s8, s2, 31
	s_lshr_b32 s8, s8, 29
	s_add_i32 s8, s2, s8
	s_ashr_i32 s9, s8, 3
	s_and_b32 s8, s8, -8
	s_sub_i32 s8, s2, s8
	s_lshl_b32 s11, s8, 7
	s_mul_i32 s10, s8, 0x81
	s_cmp_lt_i32 s8, 0
	s_cselect_b32 s8, s10, s11
	s_add_i32 s8, s8, s9
	s_xor_b32 s8, s8, 0x60
	s_lshr_b32 s10, s8, 5
	s_lshl_b32 s10, s10, 2
	s_and_b32 s9, s8, 31
	s_lshr_b32 s42, s9, 2
	s_and_b32 s9, s9, 3
	s_add_i32 s44, s10, s9

.LBB0_1545:
	s_ashr_i32 s34, s36, 3
	s_add_i32 s34, s38, s34
	s_xor_b32 s34, s34, 0x60
	s_lshr_b32 s36, s34, 5
	s_lshl_b32 s36, s36, 2
	s_and_b32 s35, s34, 31
	s_lshr_b32 s34, s35, 2
	s_and_b32 s35, s35, 3
	s_add_i32 s36, s36, s35
